# scan compute loop edge rotation: next chunk's LDS address set-up moved from the loop head into the tail between the last y write and the barrier drain
# speedup vs baseline: 1.0262x; 1.0180x over previous
.LBB0_1047:
	s_and_b64 vcc, exec, s[24:25]
	s_cbranch_vccz .LBB0_1279
	s_waitcnt vmcnt(0)
	v_mov_b32_e32 v4, v232
	s_nop 0
	v_ashrrev_i32_e32 v0, 6, v4
	v_and_b32_e32 v54, 15, v4
	v_cmp_gt_i32_e32 vcc, 4, v0
	v_lshlrev_b32_e32 v38, 2, v54
	s_barrier
	s_and_saveexec_b64 s[24:25], vcc
	s_xor_b64 s[24:25], exec, s[24:25]
	s_cbranch_execz .LBB0_1051
	v_lshlrev_b32_e32 v2, 2, v4
	s_waitcnt lgkmcnt(0)
	s_barrier
	v_and_b32_e32 v2, 0xc0, v2
	v_lshl_or_b32 v85, v0, 8, v2
	v_mov_b32_e32 v74, 0
	v_lshlrev_b32_e32 v83, 4, v54
	v_add3_u32 v87, 0, v85, v38
	s_mov_b32 s26, 0
	s_mov_b32 s96, 0x12800
	v_mov_b32_e32 v75, v74
	v_mov_b32_e32 v76, v74
	v_mov_b32_e32 v77, v74
	v_add_u32_e32 v88, 0x12800, v83
	ds_read_b128 v[108:111], v88 offset:4096
	ds_read_b128 v[100:103], v88
	ds_read_b128 v[120:123], v88 offset:8192
	ds_read_b128 v[112:115], v88 offset:4352
	ds_read_b128 v[104:107], v88 offset:256
	ds_read_b128 v[128:131], v88 offset:8448
	ds_read_b128 v[124:127], v88 offset:4608
	ds_read_b128 v[116:119], v88 offset:512
	s_waitcnt lgkmcnt(0)
	s_and_b32 s2, s26, 1
	s_mul_i32 s3, s2, 0x5400
	v_lshlrev_b32_e32 v91, 2, v87
	v_lshl_add_u32 v91, s2, 14, v91
	s_add_i32 s2, s3, 0
	v_add_u32_e32 v0, s2, v85
	v_add_u32_e32 v89, s2, v83
	v_add_u32_e32 v90, s96, v83
	s_add_i32 s96, s96, 0x3000
	s_cmp_eq_u32 s96, 0x1e800
	s_cselect_b32 s96, 0x20200, s96
	s_cmp_eq_u32 s96, 0x23200
	s_cselect_b32 s96, 0x12800, s96
	v_add_u32_e32 v88, s96, v83
	s_setprio 3
.LBB0_1050:
	ds_read_b128 v[14:17], v0 offset:20480
	ds_read_b128 v[10:13], v0 offset:20496
	ds_read_b128 v[6:9], v0 offset:20512
	ds_read_b128 v[2:5], v0 offset:20528
	ds_read_b128 v[54:57], v89 offset:16384
	ds_read_b128 v[26:29], v89 offset:16640
	ds_read_b128 v[78:81], v89 offset:4096
	ds_read_b128 v[58:61], v89 offset:4352
	ds_read_b128 v[30:33], v89 offset:4608
	ds_read_b128 v[22:25], v90 offset:8704
	ds_read_b128 v[18:21], v89 offset:16896
	v_pk_mul_f32 v[66:67], v[74:75], v[108:109]
	s_waitcnt lgkmcnt(4)
	v_pk_mul_f32 v[78:79], v[14:15], v[78:79] op_sel_hi:[0,1]
	v_pk_fma_f32 v[66:67], v[76:77], v[110:111], v[66:67]
	v_pk_mul_f32 v[80:81], v[14:15], v[80:81] op_sel_hi:[0,1]
	v_add_f32_e32 v66, v66, v67
	v_pk_fma_f32 v[62:63], v[74:75], v[100:101], v[78:79]
	v_pk_fma_f32 v[64:65], v[76:77], v[102:103], v[80:81]
	v_add_f32_dpp v66, v66, v66 quad_perm:[1,0,3,2] row_mask:0xf bank_mask:0xf bound_ctrl:1
	v_mov_b32_e32 v0, v17
	v_mov_b32_e32 v82, v13
	v_add_f32_dpp v66, v66, v66 quad_perm:[2,3,0,1] row_mask:0xf bank_mask:0xf bound_ctrl:1
	v_mov_b32_e32 v84, v9
	v_mov_b32_e32 v86, v5
	v_add_f32_dpp v66, v66, v66 row_half_mirror row_mask:0xf bank_mask:0xf bound_ctrl:1
	s_add_i32 s26, s26, 1
	v_add_f32_dpp v66, v66, v66 row_ror:8 row_mask:0xf bank_mask:0xf bound_ctrl:1
	v_pk_fma_f32 v[62:63], v[120:121], v[66:67], v[62:63] op_sel_hi:[1,0,1] neg_lo:[1,0,0] neg_hi:[1,0,0]
	v_pk_fma_f32 v[64:65], v[122:123], v[66:67], v[64:65] op_sel_hi:[1,0,1] neg_lo:[1,0,0] neg_hi:[1,0,0]
	v_pk_mul_f32 v[50:51], v[112:113], v[62:63]
	v_pk_mul_f32 v[46:47], v[104:105], v[62:63]
	v_pk_fma_f32 v[50:51], v[114:115], v[64:65], v[50:51]
	s_waitcnt lgkmcnt(3)
	v_pk_fma_f32 v[66:67], v[14:15], v[58:59], v[46:47] op_sel:[1,0,0]
	v_add_f32_e32 v47, v50, v51
	v_pk_mul_f32 v[48:49], v[106:107], v[64:65]
	v_pk_mul_f32 v[56:57], v[56:57], v[64:65]
	v_add_f32_dpp v68, v47, v47 quad_perm:[1,0,3,2] row_mask:0xf bank_mask:0xf bound_ctrl:1
	v_pk_fma_f32 v[14:15], v[14:15], v[60:61], v[48:49] op_sel:[1,0,0]
	v_pk_fma_f32 v[54:55], v[54:55], v[62:63], v[56:57]
	v_add_f32_dpp v68, v68, v68 quad_perm:[2,3,0,1] row_mask:0xf bank_mask:0xf bound_ctrl:1
	v_add_f32_e32 v92, v54, v55
	v_add_f32_dpp v68, v68, v68 row_half_mirror row_mask:0xf bank_mask:0xf bound_ctrl:1
	ds_read_b128 v[46:49], v90 offset:768
	ds_read_b128 v[50:53], v89 offset:4864
	ds_read_b128 v[54:57], v90 offset:4864
	ds_read_b128 v[58:61], v90 offset:8960
	ds_read_b128 v[62:65], v89 offset:17152
	v_add_f32_dpp v68, v68, v68 row_ror:8 row_mask:0xf bank_mask:0xf bound_ctrl:1
	v_pk_fma_f32 v[42:43], v[128:129], v[68:69], v[66:67] op_sel_hi:[1,0,1] neg_lo:[1,0,0] neg_hi:[1,0,0]
	v_pk_fma_f32 v[14:15], v[130:131], v[68:69], v[14:15] op_sel_hi:[1,0,1] neg_lo:[1,0,0] neg_hi:[1,0,0]
	v_pk_mul_f32 v[38:39], v[124:125], v[42:43]
	v_pk_mul_f32 v[28:29], v[28:29], v[14:15]
	v_pk_mul_f32 v[36:37], v[118:119], v[14:15]
	v_pk_fma_f32 v[14:15], v[126:127], v[14:15], v[38:39]
	v_pk_mul_f32 v[34:35], v[116:117], v[42:43]
	v_add_f32_e32 v14, v14, v15
	v_pk_fma_f32 v[26:27], v[26:27], v[42:43], v[28:29]
	s_waitcnt lgkmcnt(7)
	v_pk_fma_f32 v[42:43], v[16:17], v[30:31], v[34:35] op_sel_hi:[0,1,1]
	v_add_f32_dpp v66, v14, v14 quad_perm:[1,0,3,2] row_mask:0xf bank_mask:0xf bound_ctrl:1
	v_pk_fma_f32 v[44:45], v[16:17], v[32:33], v[36:37] op_sel_hi:[0,1,1]
	v_add_f32_e32 v93, v26, v27
	v_add_f32_dpp v66, v66, v66 quad_perm:[2,3,0,1] row_mask:0xf bank_mask:0xf bound_ctrl:1
	ds_read_b128 v[14:17], v90 offset:1024
	ds_read_b128 v[26:29], v89 offset:5120
	ds_read_b128 v[30:33], v90 offset:5120
	ds_read_b128 v[34:37], v90 offset:9216
	ds_read_b128 v[38:41], v89 offset:17408
	v_add_f32_dpp v66, v66, v66 row_half_mirror row_mask:0xf bank_mask:0xf bound_ctrl:1
	s_nop 1
	v_add_f32_dpp v66, v66, v66 row_ror:8 row_mask:0xf bank_mask:0xf bound_ctrl:1
	s_waitcnt lgkmcnt(11)
	v_pk_fma_f32 v[22:23], v[22:23], v[66:67], v[42:43] op_sel_hi:[1,0,1] neg_lo:[1,0,0] neg_hi:[1,0,0]
	v_pk_fma_f32 v[24:25], v[24:25], v[66:67], v[44:45] op_sel_hi:[1,0,1] neg_lo:[1,0,0] neg_hi:[1,0,0]
	s_waitcnt lgkmcnt(7)
	v_pk_mul_f32 v[42:43], v[54:55], v[22:23]
	v_pk_mul_f32 v[20:21], v[20:21], v[24:25]
	v_pk_mul_f32 v[44:45], v[46:47], v[22:23]
	v_pk_mul_f32 v[46:47], v[48:49], v[24:25]
	v_pk_fma_f32 v[18:19], v[18:19], v[22:23], v[20:21]
	v_pk_fma_f32 v[20:21], v[56:57], v[24:25], v[42:43]
	v_pk_fma_f32 v[54:55], v[0:1], v[50:51], v[44:45] op_sel_hi:[0,1,1]
	v_pk_fma_f32 v[56:57], v[0:1], v[52:53], v[46:47] op_sel_hi:[0,1,1]
	v_add_f32_e32 v94, v18, v19
	v_add_f32_e32 v18, v20, v21
	s_nop 0
	v_add_f32_dpp v0, v18, v18 quad_perm:[1,0,3,2] row_mask:0xf bank_mask:0xf bound_ctrl:1
	ds_read_b128 v[18:21], v90 offset:1280
	ds_read_b128 v[22:25], v89 offset:5376
	v_add_f32_dpp v0, v0, v0 quad_perm:[2,3,0,1] row_mask:0xf bank_mask:0xf bound_ctrl:1
	ds_read_b128 v[42:45], v90 offset:5376
	ds_read_b128 v[46:49], v90 offset:9472
	v_add_f32_dpp v0, v0, v0 row_half_mirror row_mask:0xf bank_mask:0xf bound_ctrl:1
	ds_read_b128 v[50:53], v89 offset:17664
	s_nop 0
	v_add_f32_dpp v0, v0, v0 row_ror:8 row_mask:0xf bank_mask:0xf bound_ctrl:1
	s_waitcnt lgkmcnt(11)
	v_pk_fma_f32 v[54:55], v[58:59], v[0:1], v[54:55] op_sel_hi:[1,0,1] neg_lo:[1,0,0] neg_hi:[1,0,0]
	v_pk_fma_f32 v[56:57], v[60:61], v[0:1], v[56:57] op_sel_hi:[1,0,1] neg_lo:[1,0,0] neg_hi:[1,0,0]
	s_waitcnt lgkmcnt(7)
	v_pk_mul_f32 v[30:31], v[30:31], v[54:55]
	v_pk_mul_f32 v[58:59], v[64:65], v[56:57]
	v_pk_mul_f32 v[14:15], v[14:15], v[54:55]
	v_pk_fma_f32 v[54:55], v[62:63], v[54:55], v[58:59]
	v_pk_fma_f32 v[30:31], v[32:33], v[56:57], v[30:31]
	v_pk_fma_f32 v[62:63], v[10:11], v[26:27], v[14:15] op_sel_hi:[0,1,1]
	v_add_f32_e32 v95, v54, v55
	v_add_f32_e32 v14, v30, v31
	ds_write_b128 v91, v[92:95] offset:43008
	v_pk_mul_f32 v[16:17], v[16:17], v[56:57]
	v_add_f32_dpp v0, v14, v14 quad_perm:[1,0,3,2] row_mask:0xf bank_mask:0xf bound_ctrl:1
	v_pk_fma_f32 v[64:65], v[10:11], v[28:29], v[16:17] op_sel_hi:[0,1,1]
	ds_read_b128 v[14:17], v90 offset:1536
	v_add_f32_dpp v0, v0, v0 quad_perm:[2,3,0,1] row_mask:0xf bank_mask:0xf bound_ctrl:1
	ds_read_b128 v[26:29], v89 offset:5632
	ds_read_b128 v[30:33], v90 offset:5632
	v_add_f32_dpp v0, v0, v0 row_half_mirror row_mask:0xf bank_mask:0xf bound_ctrl:1
	ds_read_b128 v[54:57], v90 offset:9728
	ds_read_b128 v[58:61], v89 offset:17920
	v_add_f32_dpp v0, v0, v0 row_ror:8 row_mask:0xf bank_mask:0xf bound_ctrl:1
	s_waitcnt lgkmcnt(12)
	v_pk_fma_f32 v[34:35], v[34:35], v[0:1], v[62:63] op_sel_hi:[1,0,1] neg_lo:[1,0,0] neg_hi:[1,0,0]
	v_pk_fma_f32 v[36:37], v[36:37], v[0:1], v[64:65] op_sel_hi:[1,0,1] neg_lo:[1,0,0] neg_hi:[1,0,0]
	s_waitcnt lgkmcnt(8)
	v_pk_mul_f32 v[42:43], v[42:43], v[34:35]
	v_pk_mul_f32 v[40:41], v[40:41], v[36:37]
	v_pk_mul_f32 v[18:19], v[18:19], v[34:35]
	v_pk_mul_f32 v[20:21], v[20:21], v[36:37]
	v_pk_fma_f32 v[34:35], v[38:39], v[34:35], v[40:41]
	v_pk_fma_f32 v[36:37], v[44:45], v[36:37], v[42:43]
	v_pk_fma_f32 v[62:63], v[10:11], v[22:23], v[18:19] op_sel:[1,0,0]
	v_add_f32_e32 v96, v34, v35
	v_add_f32_e32 v18, v36, v37
	v_pk_fma_f32 v[10:11], v[10:11], v[24:25], v[20:21] op_sel:[1,0,0]
	v_add_f32_dpp v0, v18, v18 quad_perm:[1,0,3,2] row_mask:0xf bank_mask:0xf bound_ctrl:1
	ds_read_b128 v[18:21], v90 offset:1792
	ds_read_b128 v[22:25], v89 offset:5888
	v_add_f32_dpp v0, v0, v0 quad_perm:[2,3,0,1] row_mask:0xf bank_mask:0xf bound_ctrl:1
	ds_read_b128 v[34:37], v90 offset:5888
	ds_read_b128 v[38:41], v90 offset:9984
	v_add_f32_dpp v0, v0, v0 row_half_mirror row_mask:0xf bank_mask:0xf bound_ctrl:1
	ds_read_b128 v[42:45], v89 offset:18176
	s_nop 0
	v_add_f32_dpp v0, v0, v0 row_ror:8 row_mask:0xf bank_mask:0xf bound_ctrl:1
	s_waitcnt lgkmcnt(12)
	v_pk_fma_f32 v[46:47], v[46:47], v[0:1], v[62:63] op_sel_hi:[1,0,1] neg_lo:[1,0,0] neg_hi:[1,0,0]
	v_pk_fma_f32 v[10:11], v[48:49], v[0:1], v[10:11] op_sel_hi:[1,0,1] neg_lo:[1,0,0] neg_hi:[1,0,0]
	s_waitcnt lgkmcnt(7)
	v_pk_mul_f32 v[30:31], v[30:31], v[46:47]
	v_pk_mul_f32 v[48:49], v[52:53], v[10:11]
	v_pk_mul_f32 v[14:15], v[14:15], v[46:47]
	v_pk_mul_f32 v[16:17], v[16:17], v[10:11]
	v_pk_fma_f32 v[46:47], v[50:51], v[46:47], v[48:49]
	v_pk_fma_f32 v[10:11], v[32:33], v[10:11], v[30:31]
	v_add_f32_e32 v97, v46, v47
	v_add_f32_e32 v10, v10, v11
	v_pk_fma_f32 v[50:51], v[12:13], v[26:27], v[14:15] op_sel_hi:[0,1,1]
	v_add_f32_dpp v0, v10, v10 quad_perm:[1,0,3,2] row_mask:0xf bank_mask:0xf bound_ctrl:1
	v_pk_fma_f32 v[52:53], v[12:13], v[28:29], v[16:17] op_sel_hi:[0,1,1]
	ds_read_b128 v[10:13], v90 offset:2048
	v_add_f32_dpp v0, v0, v0 quad_perm:[2,3,0,1] row_mask:0xf bank_mask:0xf bound_ctrl:1
	ds_read_b128 v[14:17], v89 offset:6144
	ds_read_b128 v[26:29], v90 offset:6144
	v_add_f32_dpp v0, v0, v0 row_half_mirror row_mask:0xf bank_mask:0xf bound_ctrl:1
	ds_read_b128 v[30:33], v90 offset:10240
	ds_read_b128 v[46:49], v89 offset:18432
	v_add_f32_dpp v0, v0, v0 row_ror:8 row_mask:0xf bank_mask:0xf bound_ctrl:1
	s_waitcnt lgkmcnt(11)
	v_pk_fma_f32 v[50:51], v[54:55], v[0:1], v[50:51] op_sel_hi:[1,0,1] neg_lo:[1,0,0] neg_hi:[1,0,0]
	v_pk_fma_f32 v[52:53], v[56:57], v[0:1], v[52:53] op_sel_hi:[1,0,1] neg_lo:[1,0,0] neg_hi:[1,0,0]
	s_waitcnt lgkmcnt(7)
	v_pk_mul_f32 v[34:35], v[34:35], v[50:51]
	v_pk_mul_f32 v[54:55], v[60:61], v[52:53]
	v_pk_mul_f32 v[18:19], v[18:19], v[50:51]
	v_pk_fma_f32 v[50:51], v[58:59], v[50:51], v[54:55]
	v_pk_fma_f32 v[34:35], v[36:37], v[52:53], v[34:35]
	v_pk_fma_f32 v[58:59], v[82:83], v[22:23], v[18:19] op_sel_hi:[0,1,1]
	v_add_f32_e32 v98, v50, v51
	v_add_f32_e32 v18, v34, v35
	v_pk_mul_f32 v[20:21], v[20:21], v[52:53]
	v_add_f32_dpp v0, v18, v18 quad_perm:[1,0,3,2] row_mask:0xf bank_mask:0xf bound_ctrl:1
	v_pk_fma_f32 v[60:61], v[82:83], v[24:25], v[20:21] op_sel_hi:[0,1,1]
	ds_read_b128 v[18:21], v90 offset:2304
	v_add_f32_dpp v0, v0, v0 quad_perm:[2,3,0,1] row_mask:0xf bank_mask:0xf bound_ctrl:1
	ds_read_b128 v[22:25], v89 offset:6400
	ds_read_b128 v[34:37], v90 offset:6400
	v_add_f32_dpp v0, v0, v0 row_half_mirror row_mask:0xf bank_mask:0xf bound_ctrl:1
	ds_read_b128 v[50:53], v90 offset:10496
	ds_read_b128 v[54:57], v89 offset:18688
	v_add_f32_dpp v0, v0, v0 row_ror:8 row_mask:0xf bank_mask:0xf bound_ctrl:1
	s_waitcnt lgkmcnt(11)
	v_pk_fma_f32 v[38:39], v[38:39], v[0:1], v[58:59] op_sel_hi:[1,0,1] neg_lo:[1,0,0] neg_hi:[1,0,0]
	v_pk_fma_f32 v[40:41], v[40:41], v[0:1], v[60:61] op_sel_hi:[1,0,1] neg_lo:[1,0,0] neg_hi:[1,0,0]
	s_waitcnt lgkmcnt(7)
	v_pk_mul_f32 v[26:27], v[26:27], v[38:39]
	v_pk_mul_f32 v[44:45], v[44:45], v[40:41]
	v_pk_mul_f32 v[10:11], v[10:11], v[38:39]
	v_pk_fma_f32 v[38:39], v[42:43], v[38:39], v[44:45]
	v_pk_fma_f32 v[26:27], v[28:29], v[40:41], v[26:27]
	v_pk_fma_f32 v[58:59], v[6:7], v[14:15], v[10:11] op_sel_hi:[0,1,1]
	v_add_f32_e32 v99, v38, v39
	v_add_f32_e32 v10, v26, v27
	ds_write_b128 v91, v[96:99] offset:47104
	v_pk_mul_f32 v[12:13], v[12:13], v[40:41]
	v_add_f32_dpp v0, v10, v10 quad_perm:[1,0,3,2] row_mask:0xf bank_mask:0xf bound_ctrl:1
	v_pk_fma_f32 v[60:61], v[6:7], v[16:17], v[12:13] op_sel_hi:[0,1,1]
	ds_read_b128 v[10:13], v90 offset:2560
	v_add_f32_dpp v0, v0, v0 quad_perm:[2,3,0,1] row_mask:0xf bank_mask:0xf bound_ctrl:1
	ds_read_b128 v[14:17], v89 offset:6656
	ds_read_b128 v[26:29], v90 offset:6656
	v_add_f32_dpp v0, v0, v0 row_half_mirror row_mask:0xf bank_mask:0xf bound_ctrl:1
	ds_read_b128 v[38:41], v90 offset:10752
	ds_read_b128 v[42:45], v89 offset:18944
	v_add_f32_dpp v0, v0, v0 row_ror:8 row_mask:0xf bank_mask:0xf bound_ctrl:1
	s_waitcnt lgkmcnt(12)
	v_pk_fma_f32 v[30:31], v[30:31], v[0:1], v[58:59] op_sel_hi:[1,0,1] neg_lo:[1,0,0] neg_hi:[1,0,0]
	v_pk_fma_f32 v[32:33], v[32:33], v[0:1], v[60:61] op_sel_hi:[1,0,1] neg_lo:[1,0,0] neg_hi:[1,0,0]
	s_waitcnt lgkmcnt(8)
	v_pk_mul_f32 v[34:35], v[34:35], v[30:31]
	v_pk_mul_f32 v[48:49], v[48:49], v[32:33]
	v_pk_mul_f32 v[18:19], v[18:19], v[30:31]
	v_pk_mul_f32 v[20:21], v[20:21], v[32:33]
	v_pk_fma_f32 v[30:31], v[46:47], v[30:31], v[48:49]
	v_pk_fma_f32 v[32:33], v[36:37], v[32:33], v[34:35]
	v_pk_fma_f32 v[58:59], v[6:7], v[22:23], v[18:19] op_sel:[1,0,0]
	v_add_f32_e32 v92, v30, v31
	v_add_f32_e32 v18, v32, v33
	v_pk_fma_f32 v[6:7], v[6:7], v[24:25], v[20:21] op_sel:[1,0,0]
	v_add_f32_dpp v0, v18, v18 quad_perm:[1,0,3,2] row_mask:0xf bank_mask:0xf bound_ctrl:1
	ds_read_b128 v[18:21], v90 offset:2816
	ds_read_b128 v[22:25], v89 offset:6912
	v_add_f32_dpp v0, v0, v0 quad_perm:[2,3,0,1] row_mask:0xf bank_mask:0xf bound_ctrl:1
	ds_read_b128 v[30:33], v90 offset:6912
	ds_read_b128 v[34:37], v90 offset:11008
	v_add_f32_dpp v0, v0, v0 row_half_mirror row_mask:0xf bank_mask:0xf bound_ctrl:1
	ds_read_b128 v[46:49], v89 offset:19200
	s_nop 0
	v_add_f32_dpp v0, v0, v0 row_ror:8 row_mask:0xf bank_mask:0xf bound_ctrl:1
	s_waitcnt lgkmcnt(12)
	v_pk_fma_f32 v[50:51], v[50:51], v[0:1], v[58:59] op_sel_hi:[1,0,1] neg_lo:[1,0,0] neg_hi:[1,0,0]
	v_pk_fma_f32 v[6:7], v[52:53], v[0:1], v[6:7] op_sel_hi:[1,0,1] neg_lo:[1,0,0] neg_hi:[1,0,0]
	s_waitcnt lgkmcnt(7)
	v_pk_mul_f32 v[26:27], v[26:27], v[50:51]
	v_pk_mul_f32 v[52:53], v[56:57], v[6:7]
	v_pk_mul_f32 v[10:11], v[10:11], v[50:51]
	v_pk_mul_f32 v[12:13], v[12:13], v[6:7]
	v_pk_fma_f32 v[50:51], v[54:55], v[50:51], v[52:53]
	v_pk_fma_f32 v[6:7], v[28:29], v[6:7], v[26:27]
	v_add_f32_e32 v93, v50, v51
	v_add_f32_e32 v6, v6, v7
	v_pk_fma_f32 v[54:55], v[8:9], v[14:15], v[10:11] op_sel_hi:[0,1,1]
	v_add_f32_dpp v0, v6, v6 quad_perm:[1,0,3,2] row_mask:0xf bank_mask:0xf bound_ctrl:1
	v_pk_fma_f32 v[56:57], v[8:9], v[16:17], v[12:13] op_sel_hi:[0,1,1]
	ds_read_b128 v[6:9], v90 offset:3072
	v_add_f32_dpp v0, v0, v0 quad_perm:[2,3,0,1] row_mask:0xf bank_mask:0xf bound_ctrl:1
	ds_read_b128 v[10:13], v89 offset:7168
	ds_read_b128 v[14:17], v90 offset:7168
	v_add_f32_dpp v0, v0, v0 row_half_mirror row_mask:0xf bank_mask:0xf bound_ctrl:1
	ds_read_b128 v[26:29], v90 offset:11264
	ds_read_b128 v[50:53], v89 offset:19456
	v_add_f32_dpp v0, v0, v0 row_ror:8 row_mask:0xf bank_mask:0xf bound_ctrl:1
	s_waitcnt lgkmcnt(11)
	v_pk_fma_f32 v[38:39], v[38:39], v[0:1], v[54:55] op_sel_hi:[1,0,1] neg_lo:[1,0,0] neg_hi:[1,0,0]
	v_pk_fma_f32 v[40:41], v[40:41], v[0:1], v[56:57] op_sel_hi:[1,0,1] neg_lo:[1,0,0] neg_hi:[1,0,0]
	s_waitcnt lgkmcnt(7)
	v_pk_mul_f32 v[30:31], v[30:31], v[38:39]
	v_pk_mul_f32 v[44:45], v[44:45], v[40:41]
	v_pk_mul_f32 v[18:19], v[18:19], v[38:39]
	v_pk_fma_f32 v[38:39], v[42:43], v[38:39], v[44:45]
	v_pk_fma_f32 v[30:31], v[32:33], v[40:41], v[30:31]
	v_pk_fma_f32 v[54:55], v[84:85], v[22:23], v[18:19] op_sel_hi:[0,1,1]
	v_add_f32_e32 v94, v38, v39
	v_add_f32_e32 v18, v30, v31
	v_pk_mul_f32 v[20:21], v[20:21], v[40:41]
	v_add_f32_dpp v0, v18, v18 quad_perm:[1,0,3,2] row_mask:0xf bank_mask:0xf bound_ctrl:1
	v_pk_fma_f32 v[56:57], v[84:85], v[24:25], v[20:21] op_sel_hi:[0,1,1]
	ds_read_b128 v[18:21], v90 offset:3328
	v_add_f32_dpp v0, v0, v0 quad_perm:[2,3,0,1] row_mask:0xf bank_mask:0xf bound_ctrl:1
	ds_read_b128 v[22:25], v89 offset:7424
	ds_read_b128 v[30:33], v90 offset:7424
	v_add_f32_dpp v0, v0, v0 row_half_mirror row_mask:0xf bank_mask:0xf bound_ctrl:1
	ds_read_b128 v[38:41], v90 offset:11520
	ds_read_b128 v[42:45], v89 offset:19712
	v_add_f32_dpp v0, v0, v0 row_ror:8 row_mask:0xf bank_mask:0xf bound_ctrl:1
	s_waitcnt lgkmcnt(11)
	v_pk_fma_f32 v[34:35], v[34:35], v[0:1], v[54:55] op_sel_hi:[1,0,1] neg_lo:[1,0,0] neg_hi:[1,0,0]
	v_pk_fma_f32 v[36:37], v[36:37], v[0:1], v[56:57] op_sel_hi:[1,0,1] neg_lo:[1,0,0] neg_hi:[1,0,0]
	s_waitcnt lgkmcnt(7)
	v_pk_mul_f32 v[14:15], v[14:15], v[34:35]
	v_pk_mul_f32 v[48:49], v[48:49], v[36:37]
	v_pk_mul_f32 v[6:7], v[6:7], v[34:35]
	v_pk_fma_f32 v[34:35], v[46:47], v[34:35], v[48:49]
	v_pk_fma_f32 v[14:15], v[16:17], v[36:37], v[14:15]
	v_pk_fma_f32 v[54:55], v[2:3], v[10:11], v[6:7] op_sel_hi:[0,1,1]
	v_add_f32_e32 v95, v34, v35
	v_add_f32_e32 v6, v14, v15
	ds_write_b128 v91, v[92:95] offset:51200
	v_pk_mul_f32 v[8:9], v[8:9], v[36:37]
	v_add_f32_dpp v0, v6, v6 quad_perm:[1,0,3,2] row_mask:0xf bank_mask:0xf bound_ctrl:1
	v_pk_fma_f32 v[56:57], v[2:3], v[12:13], v[8:9] op_sel_hi:[0,1,1]
	ds_read_b128 v[6:9], v90 offset:3584
	v_add_f32_dpp v0, v0, v0 quad_perm:[2,3,0,1] row_mask:0xf bank_mask:0xf bound_ctrl:1
	ds_read_b128 v[10:13], v89 offset:7680
	ds_read_b128 v[14:17], v90 offset:7680
	v_add_f32_dpp v0, v0, v0 row_half_mirror row_mask:0xf bank_mask:0xf bound_ctrl:1
	ds_read_b128 v[34:37], v90 offset:11776
	ds_read_b128 v[46:49], v89 offset:19968
	v_add_f32_dpp v0, v0, v0 row_ror:8 row_mask:0xf bank_mask:0xf bound_ctrl:1
	s_waitcnt lgkmcnt(12)
	v_pk_fma_f32 v[26:27], v[26:27], v[0:1], v[54:55] op_sel_hi:[1,0,1] neg_lo:[1,0,0] neg_hi:[1,0,0]
	v_pk_fma_f32 v[28:29], v[28:29], v[0:1], v[56:57] op_sel_hi:[1,0,1] neg_lo:[1,0,0] neg_hi:[1,0,0]
	s_waitcnt lgkmcnt(8)
	v_pk_mul_f32 v[30:31], v[30:31], v[26:27]
	v_pk_mul_f32 v[52:53], v[52:53], v[28:29]
	v_pk_mul_f32 v[18:19], v[18:19], v[26:27]
	v_pk_mul_f32 v[20:21], v[20:21], v[28:29]
	v_pk_fma_f32 v[26:27], v[50:51], v[26:27], v[52:53]
	v_pk_fma_f32 v[28:29], v[32:33], v[28:29], v[30:31]
	v_pk_fma_f32 v[54:55], v[2:3], v[22:23], v[18:19] op_sel:[1,0,0]
	v_add_f32_e32 v96, v26, v27
	v_add_f32_e32 v18, v28, v29
	v_pk_fma_f32 v[2:3], v[2:3], v[24:25], v[20:21] op_sel:[1,0,0]
	v_add_f32_dpp v0, v18, v18 quad_perm:[1,0,3,2] row_mask:0xf bank_mask:0xf bound_ctrl:1
	ds_read_b128 v[18:21], v90 offset:3840
	ds_read_b128 v[22:25], v89 offset:7936
	v_add_f32_dpp v0, v0, v0 quad_perm:[2,3,0,1] row_mask:0xf bank_mask:0xf bound_ctrl:1
	ds_read_b128 v[26:29], v90 offset:7936
	ds_read_b128 v[30:33], v90 offset:12032
	v_add_f32_dpp v0, v0, v0 row_half_mirror row_mask:0xf bank_mask:0xf bound_ctrl:1
	ds_read_b128 v[50:53], v89 offset:20224
	s_nop 0
	v_add_f32_dpp v0, v0, v0 row_ror:8 row_mask:0xf bank_mask:0xf bound_ctrl:1
	s_waitcnt lgkmcnt(12)
	v_pk_fma_f32 v[38:39], v[38:39], v[0:1], v[54:55] op_sel_hi:[1,0,1] neg_lo:[1,0,0] neg_hi:[1,0,0]
	v_pk_fma_f32 v[2:3], v[40:41], v[0:1], v[2:3] op_sel_hi:[1,0,1] neg_lo:[1,0,0] neg_hi:[1,0,0]
	s_waitcnt lgkmcnt(7)
	v_pk_mul_f32 v[14:15], v[14:15], v[38:39]
	v_pk_mul_f32 v[40:41], v[44:45], v[2:3]
	v_pk_mul_f32 v[8:9], v[8:9], v[2:3]
	v_pk_fma_f32 v[2:3], v[16:17], v[2:3], v[14:15]
	v_pk_mul_f32 v[6:7], v[6:7], v[38:39]
	v_add_f32_e32 v0, v2, v3
	v_pk_fma_f32 v[6:7], v[4:5], v[10:11], v[6:7] op_sel_hi:[0,1,1]
	v_pk_fma_f32 v[4:5], v[4:5], v[12:13], v[8:9] op_sel_hi:[0,1,1]
	v_add_f32_dpp v0, v0, v0 quad_perm:[1,0,3,2] row_mask:0xf bank_mask:0xf bound_ctrl:1
	v_pk_fma_f32 v[38:39], v[42:43], v[38:39], v[40:41]
	ds_read_b128 v[108:111], v88 offset:4096
	v_add_f32_dpp v0, v0, v0 quad_perm:[2,3,0,1] row_mask:0xf bank_mask:0xf bound_ctrl:1
	v_add_f32_e32 v97, v38, v39
	ds_read_b128 v[100:103], v88
	v_add_f32_dpp v0, v0, v0 row_half_mirror row_mask:0xf bank_mask:0xf bound_ctrl:1
	ds_read_b128 v[120:123], v88 offset:8192
	ds_read_b128 v[112:115], v88 offset:4352
	v_add_f32_dpp v0, v0, v0 row_ror:8 row_mask:0xf bank_mask:0xf bound_ctrl:1
	s_waitcnt lgkmcnt(10)
	v_pk_fma_f32 v[2:3], v[34:35], v[0:1], v[6:7] op_sel_hi:[1,0,1] neg_lo:[1,0,0] neg_hi:[1,0,0]
	v_pk_fma_f32 v[4:5], v[36:37], v[0:1], v[4:5] op_sel_hi:[1,0,1] neg_lo:[1,0,0] neg_hi:[1,0,0]
	s_waitcnt lgkmcnt(6)
	v_pk_mul_f32 v[8:9], v[26:27], v[2:3]
	v_pk_mul_f32 v[6:7], v[48:49], v[4:5]
	v_pk_mul_f32 v[10:11], v[18:19], v[2:3]
	v_pk_mul_f32 v[12:13], v[20:21], v[4:5]
	v_pk_fma_f32 v[2:3], v[46:47], v[2:3], v[6:7]
	v_pk_fma_f32 v[4:5], v[28:29], v[4:5], v[8:9]
	v_add_f32_e32 v98, v2, v3
	v_add_f32_e32 v2, v4, v5
	v_pk_fma_f32 v[8:9], v[86:87], v[24:25], v[12:13] op_sel_hi:[0,1,1]
	v_add_f32_dpp v0, v2, v2 quad_perm:[1,0,3,2] row_mask:0xf bank_mask:0xf bound_ctrl:1
	v_pk_fma_f32 v[6:7], v[86:87], v[22:23], v[10:11] op_sel_hi:[0,1,1]
	ds_read_b128 v[104:107], v88 offset:256
	v_add_f32_dpp v0, v0, v0 quad_perm:[2,3,0,1] row_mask:0xf bank_mask:0xf bound_ctrl:1
	ds_read_b128 v[128:131], v88 offset:8448
	ds_read_b128 v[124:127], v88 offset:4608
	v_add_f32_dpp v0, v0, v0 row_half_mirror row_mask:0xf bank_mask:0xf bound_ctrl:1
	ds_read_b128 v[116:119], v88 offset:512
	s_nop 0
	v_add_f32_dpp v0, v0, v0 row_ror:8 row_mask:0xf bank_mask:0xf bound_ctrl:1
	s_waitcnt lgkmcnt(9)
	v_pk_fma_f32 v[76:77], v[32:33], v[0:1], v[8:9] op_sel_hi:[1,0,1] neg_lo:[1,0,0] neg_hi:[1,0,0]
	v_pk_fma_f32 v[74:75], v[30:31], v[0:1], v[6:7] op_sel_hi:[1,0,1] neg_lo:[1,0,0] neg_hi:[1,0,0]
	s_waitcnt lgkmcnt(8)
	v_pk_mul_f32 v[2:3], v[52:53], v[76:77]
	s_nop 0
	v_pk_fma_f32 v[2:3], v[50:51], v[74:75], v[2:3]
	s_nop 0
	v_add_f32_e32 v99, v2, v3
	ds_write_b128 v91, v[96:99] offset:55296
	s_and_b32 s2, s26, 1
	s_mul_i32 s3, s2, 0x5400
	v_lshlrev_b32_e32 v91, 2, v87
	v_lshl_add_u32 v91, s2, 14, v91
	s_add_i32 s2, s3, 0
	v_add_u32_e32 v0, s2, v85
	v_add_u32_e32 v89, s2, v83
	v_add_u32_e32 v90, s96, v83
	s_add_i32 s96, s96, 0x3000
	s_cmp_eq_u32 s96, 0x1e800
	s_cselect_b32 s96, 0x20200, s96
	s_cmp_eq_u32 s96, 0x23200
	s_cselect_b32 s96, 0x12800, s96
	v_add_u32_e32 v88, s96, v83
	s_cmpk_eq_i32 s26, 0x110
	s_waitcnt lgkmcnt(0)
	s_barrier
	s_cbranch_scc0 .LBB0_1050
	s_setprio 0
